# v40 + down-GEMM decode: has_next inversion done with s_andn2 instead of v_cndmask/v_cmp
# speedup vs baseline: 1.0062x; 1.0062x over previous
;     __device__ bool next(int i, Unit& u) const { return S.next(i, u); }
;     __device__ bool next(int i, Unit& u) const { const int L = i * G + c; if (L >= 3 * 44) return false; u.pm = L % 3; u.pn = L / 3; u.g = 0; u.part = 0; u.keep = 0; return true; }
;     __device__ bool next(int i, Unit& u) const {
;         const long L = (long)i * G + c; if (L >= nwg) return false;
;         int wgid = (int)L; { const int q = nwg / NXCD, r = nwg % NXCD, xcd = wgid % NXCD, off = wgid / NXCD; wgid = (xcd < r ? xcd * (q + 1) : r * (q + 1) + (xcd - r) * q) + off; }
;         const int nig = WGM * nN, gid = wgid / nig, fm = gid * WGM, gsz = (nM - fm) < WGM ? (nM - fm) : WGM;
;         u.pm = fm + ((wgid % nig) % gsz); u.pn = (wgid % nig) / gsz; u.g = 0; u.part = 0; u.keep = 0; return true;
; template <class Prob, class Epi, bool I8 = false, bool ALIGN_EPI = true, bool SP2 = true>
; __device__ __forceinline__ void gemm_phase(LAS unsigned char* lds, int wave, const Prob& P, const Epi& E) {
;     ...
;         const bool has_next = P.next(ui + 1, nxt);
;         const char* nA = has_next ? P.a_tile(nxt) : cA; const char* nB = has_next ? P.b_tile(nxt) : cB;
.LBB0_1211:
	s_andn2_b64 s[36:37], exec, s[38:39]
	s_andn2_b64 vcc, exec, s[38:39]
	s_mov_b64 s[38:39], s[44:45]
	s_cbranch_vccnz .LBB0_1213
	v_readlane_b32 s4, v251, 0
	s_mul_i32 s1, s90, 0x160000
	v_readlane_b32 s6, v251, 2
	s_mul_hi_i32 s0, s90, 0x160000
	v_readlane_b32 s7, v251, 3
	s_add_u32 s38, s6, s1
	s_addc_u32 s39, s7, s0
	v_readlane_b32 s5, v251, 1
